# EpiKV V-transposed stores: 4 short stores per group merged into one dwordx2 via in-quad 4x4 transpose (DPP + v_perm + v_bfi)
# baseline (speedup 1.0000x reference)
; __device__ __forceinline__ unsigned cvt_pk(float lo, float hi) { unsigned r; asm volatile("v_cvt_pk_bf16_f32 %0, %1, %2" : "=v"(r) : "v"(lo), "v"(hi)); return r; }
; __device__ __forceinline__ u32x2 pack4(f32x4 v) { u32x2 r; r.x = cvt_pk(v[0], v[1]); r.y = cvt_pk(v[2], v[3]); return r; }
; #define FOR_AI_M _Pragma("unroll") for (int ai = 0; ai < 2; ++ai) _Pragma("unroll") for (int m = 0; m < 4; ++m)
;     __device__ __forceinline__ void operator()(EPI_ARGS) const {
;         FOR_AI_M {
;             const int row = u.pm * 256 + ai * 128 + wr * 64 + m * 16 + fr;
;             {
;                 const float rs = rsqrtf(ssq_kv[row] * (1.0f / 256.0f) + EPS);
;                 const int b = row >> 11, t = row & 2047;
; #pragma unroll
;                 for (int n = 0; n < 2; ++n) {
;                     *(u32x2*)(KN + ((size_t)row * 1024 + u.pn * 128 + wc * 32 + n * 16 + 4 * fq)) = pack4(acc[ai][0][m][n] * rs);
;                     const f32x4 v = acc[ai][1][m][n] * rs; const int d = wc * 32 + n * 16 + 4 * fq;
;                     bf16_t* vp = VT + ((size_t)((b * 8 + u.pn) * 128 + d)) * 2048 + t;
;                     const unsigned w0 = cvt_pk(v[0], v[1]), w1 = cvt_pk(v[2], v[3]);
;                     vp[0] = (bf16_t)(w0 & 0xffff); vp[2048] = (bf16_t)(w0 >> 16); vp[2 * 2048] = (bf16_t)(w1 & 0xffff); vp[3 * 2048] = (bf16_t)(w1 >> 16);
;                 }
.LBB0_565:
	v_mbcnt_lo_u32_b32 v250, -1, 0
	v_mbcnt_hi_u32_b32 v250, -1, v250
	v_mov_b32_e32 v244, 0x5040100
	v_mov_b32_e32 v252, 0x3020706
	v_and_b32_e32 v251, 1, v250
	v_bfe_i32 v245, v250, 1, 1
	v_sub_u32_e32 v253, 0, v251
	v_and_b32_e32 v250, 3, v250
	v_bfi_b32 v244, v253, v252, v244
	v_mul_u32_u24_e32 v250, 0xffe, v250
	v_mov_b32_e32 v251, 0
	v_mov_b32_e32 v136, v131
	v_mov_b32_e32 v143, v147
	s_mov_b32 s7, s16
	s_mov_b32 s10, s57
	s_lshl_b32 s6, s6, 8
	s_lshl_b32 s7, s7, 6
	s_add_i32 s7, s7, s6
	v_add_u32_e32 v142, s7, v136
	v_lshlrev_b32_e32 v154, 2, v143
	v_ashrrev_i32_e32 v143, 31, v142
	v_lshl_add_u64 v[156:157], v[142:143], 2, s[20:21]
	global_load_dword v136, v[156:157], off
	v_lshlrev_b64 v[158:159], 11, v[142:143]
	v_ashrrev_i32_e32 v143, 8, v142
	s_lshl_b32 s8, s56, 7
	s_lshl_b32 s6, s10, 5
	v_and_b32_e32 v143, 0x1fffff8, v143
	s_ashr_i32 s9, s8, 31
	v_add_u32_e32 v153, s6, v154
	v_add_u32_e32 v143, s56, v143
	s_ashr_i32 s7, s6, 31
	v_lshl_add_u32 v160, v143, 7, v153
	s_lshl_b64 s[58:59], s[8:9], 1
	v_ashrrev_i32_e32 v155, 31, v154
	s_lshl_b64 s[62:63], s[6:7], 1
	v_ashrrev_i32_e32 v161, 31, v160
	s_mov_b64 s[6:7], -1
	s_waitcnt vmcnt(0)
	v_fmamk_f32 v136, v136, 0x3b800000, v152
	v_cmp_gt_f32_e32 vcc, s78, v136
	v_mul_f32_e32 v156, 0x4b800000, v136
	s_nop 0
	v_cndmask_b32_e32 v136, v136, v156, vcc
	v_rsq_f32_e32 v136, v136
	s_nop 0
	v_mul_f32_e32 v156, 0x45800000, v136
	v_cndmask_b32_e32 v156, v136, v156, vcc
	v_pk_mul_f32 v[124:125], v[124:125], v[156:157] op_sel_hi:[1,0]
	v_pk_mul_f32 v[126:127], v[126:127], v[156:157] op_sel_hi:[1,0]
	v_cvt_pk_bf16_f32 v162, v124, v125
	v_lshl_add_u64 v[124:125], s[4:5], 0, v[158:159]
	v_lshl_add_u64 v[124:125], v[124:125], 0, s[58:59]
	v_and_b32_e32 v136, 0x7ff, v142
	v_cvt_pk_bf16_f32 v163, v126, v127
	v_lshl_add_u64 v[126:127], v[124:125], 0, s[62:63]
	v_lshlrev_b64 v[124:125], 1, v[154:155]
	v_lshlrev_b64 v[154:155], 12, v[160:161]
	v_lshl_add_u64 v[154:155], s[42:43], 0, v[154:155]
	v_lshlrev_b32_e32 v136, 1, v136
	v_lshl_add_u64 v[126:127], v[126:127], 0, v[124:125]
	v_pk_mul_f32 v[116:117], v[116:117], v[156:157] op_sel_hi:[1,0]
	v_lshl_add_u64 v[154:155], v[154:155], 0, v[136:137]
	global_store_dwordx2 v[126:127], v[162:163], off
	v_cvt_pk_bf16_f32 v143, v116, v117
	v_add_co_u32_e32 v116, vcc, s79, v154
	v_pk_mul_f32 v[118:119], v[118:119], v[156:157] op_sel_hi:[1,0]
	s_nop 0
	v_addc_co_u32_e32 v117, vcc, 0, v155, vcc
	v_cvt_pk_bf16_f32 v118, v118, v119
	v_add_co_u32_e32 v116, vcc, s44, v154
	s_nop 0
	v_addc_co_u32_e32 v117, vcc, 0, v155, vcc
	v_add_co_u32_e32 v116, vcc, s80, v154
	v_pk_mul_f32 v[112:113], v[112:113], v[156:157] op_sel_hi:[1,0]
	s_nop 0
	v_addc_co_u32_e32 v117, vcc, 0, v155, vcc
	s_nop 1
	v_mov_b32_dpp v246, v143 quad_perm:[1,0,3,2] row_mask:0xf bank_mask:0xf
	v_mov_b32_dpp v247, v118 quad_perm:[1,0,3,2] row_mask:0xf bank_mask:0xf
	v_lshl_add_u64 v[254:255], v[154:155], 0, v[250:251]
	v_perm_b32 v248, v246, v143, v244
	v_perm_b32 v249, v247, v118, v244
	v_bfi_b32 v246, v245, v248, v249
	s_nop 1
	v_mov_b32_dpp v247, v246 quad_perm:[2,3,0,1] row_mask:0xf bank_mask:0xf
	s_nop 0
	v_bfi_b32 v252, v245, v247, v248
	v_bfi_b32 v253, v245, v249, v247
	global_store_dwordx2 v[254:255], v[252:253], off
	v_pk_mul_f32 v[116:117], v[122:123], v[156:157] op_sel_hi:[1,0]
	v_pk_mul_f32 v[118:119], v[120:121], v[156:157] op_sel_hi:[1,0]
	v_pk_mul_f32 v[114:115], v[114:115], v[156:157] op_sel_hi:[1,0]
	v_cvt_pk_bf16_f32 v118, v118, v119
	v_cvt_pk_bf16_f32 v119, v116, v117
	v_add_u32_e32 v116, 16, v160
	v_ashrrev_i32_e32 v117, 31, v116
	v_lshlrev_b64 v[116:117], 12, v[116:117]
	v_lshl_add_u64 v[116:117], s[42:43], 0, v[116:117]
	v_lshl_add_u64 v[116:117], v[116:117], 0, v[136:137]
	global_store_dwordx2 v[126:127], v[118:119], off offset:32
	v_cvt_pk_bf16_f32 v118, v112, v113
	v_add_co_u32_e32 v112, vcc, s79, v116
	v_cvt_pk_bf16_f32 v114, v114, v115
	s_nop 0
	v_addc_co_u32_e32 v113, vcc, 0, v117, vcc
	v_add_co_u32_e32 v112, vcc, s44, v116
	s_nop 1
	v_addc_co_u32_e32 v113, vcc, 0, v117, vcc
	v_add_co_u32_e32 v112, vcc, s80, v116
	s_nop 1
	v_addc_co_u32_e32 v113, vcc, 0, v117, vcc
	s_nop 1
	v_mov_b32_dpp v246, v118 quad_perm:[1,0,3,2] row_mask:0xf bank_mask:0xf
	v_mov_b32_dpp v247, v114 quad_perm:[1,0,3,2] row_mask:0xf bank_mask:0xf
	v_lshl_add_u64 v[254:255], v[116:117], 0, v[250:251]
	v_perm_b32 v248, v246, v118, v244
	v_perm_b32 v249, v247, v114, v244
	v_bfi_b32 v246, v245, v248, v249
	s_nop 1
	v_mov_b32_dpp v247, v246 quad_perm:[2,3,0,1] row_mask:0xf bank_mask:0xf
	s_nop 0
	v_bfi_b32 v252, v245, v247, v248
	v_bfi_b32 v253, v245, v249, v247
	global_store_dwordx2 v[254:255], v[252:253], off
	v_add_u32_e32 v112, 16, v142
	v_ashrrev_i32_e32 v113, 31, v112
	v_lshl_add_u64 v[114:115], v[112:113], 2, s[20:21]
	global_load_dword v114, v[114:115], off
	v_lshlrev_b64 v[116:117], 11, v[112:113]
	s_waitcnt vmcnt(0)
; __device__ __forceinline__ unsigned cvt_pk(float lo, float hi) { unsigned r; asm volatile("v_cvt_pk_bf16_f32 %0, %1, %2" : "=v"(r) : "v"(lo), "v"(hi)); return r; }
; __device__ __forceinline__ u32x2 pack4(f32x4 v) { u32x2 r; r.x = cvt_pk(v[0], v[1]); r.y = cvt_pk(v[2], v[3]); return r; }
; #define FOR_AI_M _Pragma("unroll") for (int ai = 0; ai < 2; ++ai) _Pragma("unroll") for (int m = 0; m < 4; ++m)
;     __device__ __forceinline__ void operator()(EPI_ARGS) const {
;         FOR_AI_M {
;             const int row = u.pm * 256 + ai * 128 + wr * 64 + m * 16 + fr;
;             {
;                 const float rs = rsqrtf(ssq_kv[row] * (1.0f / 256.0f) + EPS);
;                 const int b = row >> 11, t = row & 2047;
; #pragma unroll
;                 for (int n = 0; n < 2; ++n) {
;                     *(u32x2*)(KN + ((size_t)row * 1024 + u.pn * 128 + wc * 32 + n * 16 + 4 * fq)) = pack4(acc[ai][0][m][n] * rs);
;                     const f32x4 v = acc[ai][1][m][n] * rs; const int d = wc * 32 + n * 16 + 4 * fq;
;                     bf16_t* vp = VT + ((size_t)((b * 8 + u.pn) * 128 + d)) * 2048 + t;
;                     const unsigned w0 = cvt_pk(v[0], v[1]), w1 = cvt_pk(v[2], v[3]);
;                     vp[0] = (bf16_t)(w0 & 0xffff); vp[2048] = (bf16_t)(w0 >> 16); vp[2 * 2048] = (bf16_t)(w1 & 0xffff); vp[3 * 2048] = (bf16_t)(w1 >> 16);
;                 }
	v_fmamk_f32 v114, v114, 0x3b800000, v152
	v_cmp_gt_f32_e32 vcc, s78, v114
	v_mul_f32_e32 v115, 0x4b800000, v114
	s_nop 0
	v_cndmask_b32_e32 v114, v114, v115, vcc
	v_rsq_f32_e32 v114, v114
	s_nop 0
	v_mul_f32_e32 v115, 0x45800000, v114
	v_cndmask_b32_e32 v114, v114, v115, vcc
	v_and_b32_e32 v115, 0x7ff, v112
	v_ashrrev_i32_e32 v112, 8, v112
	v_pk_mul_f32 v[110:111], v[110:111], v[114:115] op_sel_hi:[1,0]
	v_pk_mul_f32 v[108:109], v[108:109], v[114:115] op_sel_hi:[1,0]
	v_and_b32_e32 v112, 0x1fffff8, v112
	v_cvt_pk_bf16_f32 v108, v108, v109
	v_cvt_pk_bf16_f32 v109, v110, v111
	v_lshl_add_u64 v[110:111], s[4:5], 0, v[116:117]
	v_add_u32_e32 v112, s56, v112
	v_lshl_add_u64 v[110:111], v[110:111], 0, s[58:59]
	v_lshl_add_u32 v112, v112, 7, v153
	v_lshl_add_u64 v[110:111], v[110:111], 0, s[62:63]
	v_lshl_add_u64 v[110:111], v[110:111], 0, v[124:125]
	v_ashrrev_i32_e32 v113, 31, v112
	global_store_dwordx2 v[110:111], v[108:109], off
	v_lshlrev_b64 v[108:109], 12, v[112:113]
	v_lshl_add_u64 v[108:109], s[42:43], 0, v[108:109]
	v_lshlrev_b32_e32 v136, 1, v115
	v_pk_mul_f32 v[100:101], v[100:101], v[114:115] op_sel_hi:[1,0]
	v_lshl_add_u64 v[108:109], v[108:109], 0, v[136:137]
	v_cvt_pk_bf16_f32 v113, v100, v101
	v_add_co_u32_e32 v100, vcc, s79, v108
	v_pk_mul_f32 v[102:103], v[102:103], v[114:115] op_sel_hi:[1,0]
	s_nop 0
	v_addc_co_u32_e32 v101, vcc, 0, v109, vcc
	v_cvt_pk_bf16_f32 v102, v102, v103
	v_add_co_u32_e32 v100, vcc, s44, v108
	s_nop 0
	v_addc_co_u32_e32 v101, vcc, 0, v109, vcc
	v_add_co_u32_e32 v100, vcc, s80, v108
	v_pk_mul_f32 v[96:97], v[96:97], v[114:115] op_sel_hi:[1,0]
	s_nop 0
	v_addc_co_u32_e32 v101, vcc, 0, v109, vcc
	s_nop 1
	v_mov_b32_dpp v246, v113 quad_perm:[1,0,3,2] row_mask:0xf bank_mask:0xf
	v_mov_b32_dpp v247, v102 quad_perm:[1,0,3,2] row_mask:0xf bank_mask:0xf
	v_lshl_add_u64 v[254:255], v[108:109], 0, v[250:251]
	v_perm_b32 v248, v246, v113, v244
	v_perm_b32 v249, v247, v102, v244
	v_bfi_b32 v246, v245, v248, v249
	s_nop 1
	v_mov_b32_dpp v247, v246 quad_perm:[2,3,0,1] row_mask:0xf bank_mask:0xf
	s_nop 0
	v_bfi_b32 v252, v245, v247, v248
	v_bfi_b32 v253, v245, v249, v247
	global_store_dwordx2 v[254:255], v[252:253], off
	v_pk_mul_f32 v[100:101], v[106:107], v[114:115] op_sel_hi:[1,0]
	v_pk_mul_f32 v[102:103], v[104:105], v[114:115] op_sel_hi:[1,0]
	v_pk_mul_f32 v[98:99], v[98:99], v[114:115] op_sel_hi:[1,0]
	v_cvt_pk_bf16_f32 v102, v102, v103
	v_cvt_pk_bf16_f32 v103, v100, v101
	v_add_u32_e32 v100, 16, v112
	v_ashrrev_i32_e32 v101, 31, v100
	v_lshlrev_b64 v[100:101], 12, v[100:101]
	v_lshl_add_u64 v[100:101], s[42:43], 0, v[100:101]
	v_lshl_add_u64 v[100:101], v[100:101], 0, v[136:137]
	global_store_dwordx2 v[110:111], v[102:103], off offset:32
	v_cvt_pk_bf16_f32 v102, v96, v97
	v_add_co_u32_e32 v96, vcc, s79, v100
	v_cvt_pk_bf16_f32 v98, v98, v99
	s_nop 0
	v_addc_co_u32_e32 v97, vcc, 0, v101, vcc
	v_add_co_u32_e32 v96, vcc, s44, v100
	s_nop 1
	v_addc_co_u32_e32 v97, vcc, 0, v101, vcc
	v_add_co_u32_e32 v96, vcc, s80, v100
	s_nop 1
	v_addc_co_u32_e32 v97, vcc, 0, v101, vcc
	s_nop 1
	v_mov_b32_dpp v246, v102 quad_perm:[1,0,3,2] row_mask:0xf bank_mask:0xf
	v_mov_b32_dpp v247, v98 quad_perm:[1,0,3,2] row_mask:0xf bank_mask:0xf
	v_lshl_add_u64 v[254:255], v[100:101], 0, v[250:251]
	v_perm_b32 v248, v246, v102, v244
	v_perm_b32 v249, v247, v98, v244
	v_bfi_b32 v246, v245, v248, v249
	s_nop 1
	v_mov_b32_dpp v247, v246 quad_perm:[2,3,0,1] row_mask:0xf bank_mask:0xf
	s_nop 0
	v_bfi_b32 v252, v245, v247, v248
	v_bfi_b32 v253, v245, v249, v247
	global_store_dwordx2 v[254:255], v[252:253], off
	v_add_u32_e32 v96, 32, v142
	v_ashrrev_i32_e32 v97, 31, v96
	v_lshl_add_u64 v[98:99], v[96:97], 2, s[20:21]
	global_load_dword v98, v[98:99], off
	v_lshlrev_b64 v[100:101], 11, v[96:97]
	s_waitcnt vmcnt(0)
	v_fmamk_f32 v98, v98, 0x3b800000, v152
	v_cmp_gt_f32_e32 vcc, s78, v98
	v_mul_f32_e32 v99, 0x4b800000, v98
	s_nop 0
	v_cndmask_b32_e32 v98, v98, v99, vcc
	v_rsq_f32_e32 v98, v98
	s_nop 0
	v_mul_f32_e32 v99, 0x45800000, v98
	v_cndmask_b32_e32 v98, v98, v99, vcc
	v_and_b32_e32 v99, 0x7ff, v96
	v_ashrrev_i32_e32 v96, 8, v96
	v_pk_mul_f32 v[94:95], v[94:95], v[98:99] op_sel_hi:[1,0]
	v_pk_mul_f32 v[92:93], v[92:93], v[98:99] op_sel_hi:[1,0]
	v_and_b32_e32 v96, 0x1fffff8, v96
	v_cvt_pk_bf16_f32 v92, v92, v93
	v_cvt_pk_bf16_f32 v93, v94, v95
	v_lshl_add_u64 v[94:95], s[4:5], 0, v[100:101]
	v_add_u32_e32 v96, s56, v96
	v_lshl_add_u64 v[94:95], v[94:95], 0, s[58:59]
	v_lshl_add_u32 v96, v96, 7, v153
	v_lshl_add_u64 v[94:95], v[94:95], 0, s[62:63]
	v_lshl_add_u64 v[94:95], v[94:95], 0, v[124:125]
	v_ashrrev_i32_e32 v97, 31, v96
	global_store_dwordx2 v[94:95], v[92:93], off
	v_lshlrev_b64 v[92:93], 12, v[96:97]
	v_lshl_add_u64 v[92:93], s[42:43], 0, v[92:93]
	v_lshlrev_b32_e32 v136, 1, v99
	v_pk_mul_f32 v[84:85], v[84:85], v[98:99] op_sel_hi:[1,0]
	v_lshl_add_u64 v[92:93], v[92:93], 0, v[136:137]
	v_cvt_pk_bf16_f32 v97, v84, v85
	v_add_co_u32_e32 v84, vcc, s79, v92
	v_pk_mul_f32 v[86:87], v[86:87], v[98:99] op_sel_hi:[1,0]
	s_nop 0
	v_addc_co_u32_e32 v85, vcc, 0, v93, vcc
	v_cvt_pk_bf16_f32 v86, v86, v87
	v_add_co_u32_e32 v84, vcc, s44, v92
	s_nop 0
	v_addc_co_u32_e32 v85, vcc, 0, v93, vcc
	v_add_co_u32_e32 v84, vcc, s80, v92
	v_pk_mul_f32 v[80:81], v[80:81], v[98:99] op_sel_hi:[1,0]
	s_nop 0
	v_addc_co_u32_e32 v85, vcc, 0, v93, vcc
	s_nop 1
	v_mov_b32_dpp v246, v97 quad_perm:[1,0,3,2] row_mask:0xf bank_mask:0xf
	v_mov_b32_dpp v247, v86 quad_perm:[1,0,3,2] row_mask:0xf bank_mask:0xf
	v_lshl_add_u64 v[254:255], v[92:93], 0, v[250:251]
	v_perm_b32 v248, v246, v97, v244
	v_perm_b32 v249, v247, v86, v244
	v_bfi_b32 v246, v245, v248, v249
	s_nop 1
; __device__ __forceinline__ unsigned cvt_pk(float lo, float hi) { unsigned r; asm volatile("v_cvt_pk_bf16_f32 %0, %1, %2" : "=v"(r) : "v"(lo), "v"(hi)); return r; }
; __device__ __forceinline__ u32x2 pack4(f32x4 v) { u32x2 r; r.x = cvt_pk(v[0], v[1]); r.y = cvt_pk(v[2], v[3]); return r; }
; #define FOR_AI_M _Pragma("unroll") for (int ai = 0; ai < 2; ++ai) _Pragma("unroll") for (int m = 0; m < 4; ++m)
;     __device__ __forceinline__ void operator()(EPI_ARGS) const {
;         FOR_AI_M {
;             const int row = u.pm * 256 + ai * 128 + wr * 64 + m * 16 + fr;
;             {
;                 const float rs = rsqrtf(ssq_kv[row] * (1.0f / 256.0f) + EPS);
;                 const int b = row >> 11, t = row & 2047;
; #pragma unroll
;                 for (int n = 0; n < 2; ++n) {
;                     *(u32x2*)(KN + ((size_t)row * 1024 + u.pn * 128 + wc * 32 + n * 16 + 4 * fq)) = pack4(acc[ai][0][m][n] * rs);
;                     const f32x4 v = acc[ai][1][m][n] * rs; const int d = wc * 32 + n * 16 + 4 * fq;
;                     bf16_t* vp = VT + ((size_t)((b * 8 + u.pn) * 128 + d)) * 2048 + t;
;                     const unsigned w0 = cvt_pk(v[0], v[1]), w1 = cvt_pk(v[2], v[3]);
;                     vp[0] = (bf16_t)(w0 & 0xffff); vp[2048] = (bf16_t)(w0 >> 16); vp[2 * 2048] = (bf16_t)(w1 & 0xffff); vp[3 * 2048] = (bf16_t)(w1 >> 16);
;                 }
	v_mov_b32_dpp v247, v246 quad_perm:[2,3,0,1] row_mask:0xf bank_mask:0xf
	s_nop 0
	v_bfi_b32 v252, v245, v247, v248
	v_bfi_b32 v253, v245, v249, v247
	global_store_dwordx2 v[254:255], v[252:253], off
	v_pk_mul_f32 v[84:85], v[90:91], v[98:99] op_sel_hi:[1,0]
	v_pk_mul_f32 v[86:87], v[88:89], v[98:99] op_sel_hi:[1,0]
	v_pk_mul_f32 v[82:83], v[82:83], v[98:99] op_sel_hi:[1,0]
	v_cvt_pk_bf16_f32 v86, v86, v87
	v_cvt_pk_bf16_f32 v87, v84, v85
	v_add_u32_e32 v84, 16, v96
	v_ashrrev_i32_e32 v85, 31, v84
	v_lshlrev_b64 v[84:85], 12, v[84:85]
	v_lshl_add_u64 v[84:85], s[42:43], 0, v[84:85]
	v_lshl_add_u64 v[84:85], v[84:85], 0, v[136:137]
	global_store_dwordx2 v[94:95], v[86:87], off offset:32
	v_cvt_pk_bf16_f32 v86, v80, v81
	v_add_co_u32_e32 v80, vcc, s79, v84
	v_cvt_pk_bf16_f32 v82, v82, v83
	s_nop 0
	v_addc_co_u32_e32 v81, vcc, 0, v85, vcc
	v_add_co_u32_e32 v80, vcc, s44, v84
	s_nop 1
	v_addc_co_u32_e32 v81, vcc, 0, v85, vcc
	v_add_co_u32_e32 v80, vcc, s80, v84
	s_nop 1
	v_addc_co_u32_e32 v81, vcc, 0, v85, vcc
	s_nop 1
	v_mov_b32_dpp v246, v86 quad_perm:[1,0,3,2] row_mask:0xf bank_mask:0xf
	v_mov_b32_dpp v247, v82 quad_perm:[1,0,3,2] row_mask:0xf bank_mask:0xf
	v_lshl_add_u64 v[254:255], v[84:85], 0, v[250:251]
	v_perm_b32 v248, v246, v86, v244
	v_perm_b32 v249, v247, v82, v244
	v_bfi_b32 v246, v245, v248, v249
	s_nop 1
	v_mov_b32_dpp v247, v246 quad_perm:[2,3,0,1] row_mask:0xf bank_mask:0xf
	s_nop 0
	v_bfi_b32 v252, v245, v247, v248
	v_bfi_b32 v253, v245, v249, v247
	global_store_dwordx2 v[254:255], v[252:253], off
	v_add_u32_e32 v80, 48, v142
	v_ashrrev_i32_e32 v81, 31, v80
	v_lshl_add_u64 v[82:83], v[80:81], 2, s[20:21]
	global_load_dword v82, v[82:83], off
	v_lshlrev_b64 v[84:85], 11, v[80:81]
	s_waitcnt vmcnt(0)
	v_fmamk_f32 v82, v82, 0x3b800000, v152
	v_cmp_gt_f32_e32 vcc, s78, v82
	v_mul_f32_e32 v83, 0x4b800000, v82
	s_nop 0
	v_cndmask_b32_e32 v82, v82, v83, vcc
	v_rsq_f32_e32 v82, v82
	s_nop 0
	v_mul_f32_e32 v83, 0x45800000, v82
	v_cndmask_b32_e32 v82, v82, v83, vcc
	v_and_b32_e32 v83, 0x7ff, v80
	v_ashrrev_i32_e32 v80, 8, v80
	v_pk_mul_f32 v[78:79], v[78:79], v[82:83] op_sel_hi:[1,0]
	v_pk_mul_f32 v[76:77], v[76:77], v[82:83] op_sel_hi:[1,0]
	v_and_b32_e32 v80, 0x1fffff8, v80
	v_cvt_pk_bf16_f32 v76, v76, v77
	v_cvt_pk_bf16_f32 v77, v78, v79
	v_lshl_add_u64 v[78:79], s[4:5], 0, v[84:85]
	v_add_u32_e32 v80, s56, v80
	v_lshl_add_u64 v[78:79], v[78:79], 0, s[58:59]
	v_lshl_add_u32 v80, v80, 7, v153
	v_lshl_add_u64 v[78:79], v[78:79], 0, s[62:63]
	v_lshl_add_u64 v[78:79], v[78:79], 0, v[124:125]
	v_ashrrev_i32_e32 v81, 31, v80
	global_store_dwordx2 v[78:79], v[76:77], off
	v_lshlrev_b64 v[76:77], 12, v[80:81]
	v_lshl_add_u64 v[76:77], s[42:43], 0, v[76:77]
	v_lshlrev_b32_e32 v136, 1, v83
	v_pk_mul_f32 v[68:69], v[68:69], v[82:83] op_sel_hi:[1,0]
	v_lshl_add_u64 v[76:77], v[76:77], 0, v[136:137]
	v_cvt_pk_bf16_f32 v81, v68, v69
	v_add_co_u32_e32 v68, vcc, s79, v76
	v_pk_mul_f32 v[70:71], v[70:71], v[82:83] op_sel_hi:[1,0]
	s_nop 0
	v_addc_co_u32_e32 v69, vcc, 0, v77, vcc
	v_cvt_pk_bf16_f32 v70, v70, v71
	v_add_co_u32_e32 v68, vcc, s44, v76
	s_nop 0
	v_addc_co_u32_e32 v69, vcc, 0, v77, vcc
	v_add_co_u32_e32 v68, vcc, s80, v76
	v_pk_mul_f32 v[64:65], v[64:65], v[82:83] op_sel_hi:[1,0]
	s_nop 0
	v_addc_co_u32_e32 v69, vcc, 0, v77, vcc
	s_nop 1
	v_mov_b32_dpp v246, v81 quad_perm:[1,0,3,2] row_mask:0xf bank_mask:0xf
	v_mov_b32_dpp v247, v70 quad_perm:[1,0,3,2] row_mask:0xf bank_mask:0xf
	v_lshl_add_u64 v[254:255], v[76:77], 0, v[250:251]
	v_perm_b32 v248, v246, v81, v244
	v_perm_b32 v249, v247, v70, v244
	v_bfi_b32 v246, v245, v248, v249
	s_nop 1
	v_mov_b32_dpp v247, v246 quad_perm:[2,3,0,1] row_mask:0xf bank_mask:0xf
	s_nop 0
	v_bfi_b32 v252, v245, v247, v248
	v_bfi_b32 v253, v245, v249, v247
	global_store_dwordx2 v[254:255], v[252:253], off
	v_pk_mul_f32 v[68:69], v[74:75], v[82:83] op_sel_hi:[1,0]
	v_pk_mul_f32 v[70:71], v[72:73], v[82:83] op_sel_hi:[1,0]
	v_pk_mul_f32 v[66:67], v[66:67], v[82:83] op_sel_hi:[1,0]
	v_cvt_pk_bf16_f32 v70, v70, v71
	v_cvt_pk_bf16_f32 v71, v68, v69
	v_add_u32_e32 v68, 16, v80
	v_ashrrev_i32_e32 v69, 31, v68
	v_lshlrev_b64 v[68:69], 12, v[68:69]
	v_lshl_add_u64 v[68:69], s[42:43], 0, v[68:69]
	v_lshl_add_u64 v[68:69], v[68:69], 0, v[136:137]
	global_store_dwordx2 v[78:79], v[70:71], off offset:32
	v_cvt_pk_bf16_f32 v70, v64, v65
	v_add_co_u32_e32 v64, vcc, s79, v68
	v_cvt_pk_bf16_f32 v66, v66, v67
	s_nop 0
	v_addc_co_u32_e32 v65, vcc, 0, v69, vcc
	v_add_co_u32_e32 v64, vcc, s44, v68
	s_nop 1
	v_addc_co_u32_e32 v65, vcc, 0, v69, vcc
	v_add_co_u32_e32 v64, vcc, s80, v68
	s_nop 1
	v_addc_co_u32_e32 v65, vcc, 0, v69, vcc
	s_nop 1
	v_mov_b32_dpp v246, v70 quad_perm:[1,0,3,2] row_mask:0xf bank_mask:0xf
	v_mov_b32_dpp v247, v66 quad_perm:[1,0,3,2] row_mask:0xf bank_mask:0xf
	v_lshl_add_u64 v[254:255], v[68:69], 0, v[250:251]
	v_perm_b32 v248, v246, v70, v244
	v_perm_b32 v249, v247, v66, v244
	v_bfi_b32 v246, v245, v248, v249
	s_nop 1
	v_mov_b32_dpp v247, v246 quad_perm:[2,3,0,1] row_mask:0xf bank_mask:0xf
	s_nop 0
	v_bfi_b32 v252, v245, v247, v248
	v_bfi_b32 v253, v245, v249, v247
	global_store_dwordx2 v[254:255], v[252:253], off
	v_add_u32_e32 v64, 0x80, v142
	v_ashrrev_i32_e32 v65, 31, v64
	v_lshl_add_u64 v[66:67], v[64:65], 2, s[20:21]
	global_load_dword v66, v[66:67], off
	v_lshlrev_b64 v[68:69], 11, v[64:65]
	s_waitcnt vmcnt(0)
; __device__ __forceinline__ unsigned cvt_pk(float lo, float hi) { unsigned r; asm volatile("v_cvt_pk_bf16_f32 %0, %1, %2" : "=v"(r) : "v"(lo), "v"(hi)); return r; }
; __device__ __forceinline__ u32x2 pack4(f32x4 v) { u32x2 r; r.x = cvt_pk(v[0], v[1]); r.y = cvt_pk(v[2], v[3]); return r; }
; #define FOR_AI_M _Pragma("unroll") for (int ai = 0; ai < 2; ++ai) _Pragma("unroll") for (int m = 0; m < 4; ++m)
;     __device__ __forceinline__ void operator()(EPI_ARGS) const {
;         FOR_AI_M {
;             const int row = u.pm * 256 + ai * 128 + wr * 64 + m * 16 + fr;
;             {
;                 const float rs = rsqrtf(ssq_kv[row] * (1.0f / 256.0f) + EPS);
;                 const int b = row >> 11, t = row & 2047;
; #pragma unroll
;                 for (int n = 0; n < 2; ++n) {
;                     *(u32x2*)(KN + ((size_t)row * 1024 + u.pn * 128 + wc * 32 + n * 16 + 4 * fq)) = pack4(acc[ai][0][m][n] * rs);
;                     const f32x4 v = acc[ai][1][m][n] * rs; const int d = wc * 32 + n * 16 + 4 * fq;
;                     bf16_t* vp = VT + ((size_t)((b * 8 + u.pn) * 128 + d)) * 2048 + t;
;                     const unsigned w0 = cvt_pk(v[0], v[1]), w1 = cvt_pk(v[2], v[3]);
;                     vp[0] = (bf16_t)(w0 & 0xffff); vp[2048] = (bf16_t)(w0 >> 16); vp[2 * 2048] = (bf16_t)(w1 & 0xffff); vp[3 * 2048] = (bf16_t)(w1 >> 16);
;                 }
	v_fmamk_f32 v66, v66, 0x3b800000, v152
	v_cmp_gt_f32_e32 vcc, s78, v66
	v_mul_f32_e32 v67, 0x4b800000, v66
	s_nop 0
	v_cndmask_b32_e32 v66, v66, v67, vcc
	v_rsq_f32_e32 v66, v66
	s_nop 0
	v_mul_f32_e32 v67, 0x45800000, v66
	v_cndmask_b32_e32 v66, v66, v67, vcc
	v_and_b32_e32 v67, 0x7ff, v64
	v_ashrrev_i32_e32 v64, 8, v64
	v_pk_mul_f32 v[62:63], v[62:63], v[66:67] op_sel_hi:[1,0]
	v_pk_mul_f32 v[60:61], v[60:61], v[66:67] op_sel_hi:[1,0]
	v_and_b32_e32 v64, 0x1fffff8, v64
	v_cvt_pk_bf16_f32 v60, v60, v61
	v_cvt_pk_bf16_f32 v61, v62, v63
	v_lshl_add_u64 v[62:63], s[4:5], 0, v[68:69]
	v_add_u32_e32 v64, s56, v64
	v_lshl_add_u64 v[62:63], v[62:63], 0, s[58:59]
	v_lshl_add_u32 v64, v64, 7, v153
	v_lshl_add_u64 v[62:63], v[62:63], 0, s[62:63]
	v_lshl_add_u64 v[62:63], v[62:63], 0, v[124:125]
	v_ashrrev_i32_e32 v65, 31, v64
	global_store_dwordx2 v[62:63], v[60:61], off
	v_lshlrev_b64 v[60:61], 12, v[64:65]
	v_lshl_add_u64 v[60:61], s[42:43], 0, v[60:61]
	v_lshlrev_b32_e32 v136, 1, v67
	v_pk_mul_f32 v[52:53], v[52:53], v[66:67] op_sel_hi:[1,0]
	v_lshl_add_u64 v[60:61], v[60:61], 0, v[136:137]
	v_cvt_pk_bf16_f32 v65, v52, v53
	v_add_co_u32_e32 v52, vcc, s79, v60
	v_pk_mul_f32 v[54:55], v[54:55], v[66:67] op_sel_hi:[1,0]
	s_nop 0
	v_addc_co_u32_e32 v53, vcc, 0, v61, vcc
	v_cvt_pk_bf16_f32 v54, v54, v55
	v_add_co_u32_e32 v52, vcc, s44, v60
	s_nop 0
	v_addc_co_u32_e32 v53, vcc, 0, v61, vcc
	v_add_co_u32_e32 v52, vcc, s80, v60
	v_pk_mul_f32 v[48:49], v[48:49], v[66:67] op_sel_hi:[1,0]
	s_nop 0
	v_addc_co_u32_e32 v53, vcc, 0, v61, vcc
	s_nop 1
	v_mov_b32_dpp v246, v65 quad_perm:[1,0,3,2] row_mask:0xf bank_mask:0xf
	v_mov_b32_dpp v247, v54 quad_perm:[1,0,3,2] row_mask:0xf bank_mask:0xf
	v_lshl_add_u64 v[254:255], v[60:61], 0, v[250:251]
	v_perm_b32 v248, v246, v65, v244
	v_perm_b32 v249, v247, v54, v244
	v_bfi_b32 v246, v245, v248, v249
	s_nop 1
	v_mov_b32_dpp v247, v246 quad_perm:[2,3,0,1] row_mask:0xf bank_mask:0xf
	s_nop 0
	v_bfi_b32 v252, v245, v247, v248
	v_bfi_b32 v253, v245, v249, v247
	global_store_dwordx2 v[254:255], v[252:253], off
	v_pk_mul_f32 v[52:53], v[58:59], v[66:67] op_sel_hi:[1,0]
	v_pk_mul_f32 v[54:55], v[56:57], v[66:67] op_sel_hi:[1,0]
	v_pk_mul_f32 v[50:51], v[50:51], v[66:67] op_sel_hi:[1,0]
	v_cvt_pk_bf16_f32 v54, v54, v55
	v_cvt_pk_bf16_f32 v55, v52, v53
	v_add_u32_e32 v52, 16, v64
	v_ashrrev_i32_e32 v53, 31, v52
	v_lshlrev_b64 v[52:53], 12, v[52:53]
	v_lshl_add_u64 v[52:53], s[42:43], 0, v[52:53]
	v_lshl_add_u64 v[52:53], v[52:53], 0, v[136:137]
	global_store_dwordx2 v[62:63], v[54:55], off offset:32
	v_cvt_pk_bf16_f32 v54, v48, v49
	v_add_co_u32_e32 v48, vcc, s79, v52
	v_cvt_pk_bf16_f32 v50, v50, v51
	s_nop 0
	v_addc_co_u32_e32 v49, vcc, 0, v53, vcc
	v_add_co_u32_e32 v48, vcc, s44, v52
	s_nop 1
	v_addc_co_u32_e32 v49, vcc, 0, v53, vcc
	v_add_co_u32_e32 v48, vcc, s80, v52
	s_nop 1
	v_addc_co_u32_e32 v49, vcc, 0, v53, vcc
	s_nop 1
	v_mov_b32_dpp v246, v54 quad_perm:[1,0,3,2] row_mask:0xf bank_mask:0xf
	v_mov_b32_dpp v247, v50 quad_perm:[1,0,3,2] row_mask:0xf bank_mask:0xf
	v_lshl_add_u64 v[254:255], v[52:53], 0, v[250:251]
	v_perm_b32 v248, v246, v54, v244
	v_perm_b32 v249, v247, v50, v244
	v_bfi_b32 v246, v245, v248, v249
	s_nop 1
	v_mov_b32_dpp v247, v246 quad_perm:[2,3,0,1] row_mask:0xf bank_mask:0xf
	s_nop 0
	v_bfi_b32 v252, v245, v247, v248
	v_bfi_b32 v253, v245, v249, v247
	global_store_dwordx2 v[254:255], v[252:253], off
	v_add_u32_e32 v48, 0x90, v142
	v_ashrrev_i32_e32 v49, 31, v48
	v_lshl_add_u64 v[50:51], v[48:49], 2, s[20:21]
	global_load_dword v50, v[50:51], off
	v_lshlrev_b64 v[52:53], 11, v[48:49]
	s_waitcnt vmcnt(0)
	v_fmamk_f32 v50, v50, 0x3b800000, v152
	v_cmp_gt_f32_e32 vcc, s78, v50
	v_mul_f32_e32 v51, 0x4b800000, v50
	s_nop 0
	v_cndmask_b32_e32 v50, v50, v51, vcc
	v_rsq_f32_e32 v50, v50
	s_nop 0
	v_mul_f32_e32 v51, 0x45800000, v50
	v_cndmask_b32_e32 v50, v50, v51, vcc
	v_and_b32_e32 v51, 0x7ff, v48
	v_ashrrev_i32_e32 v48, 8, v48
	v_pk_mul_f32 v[46:47], v[46:47], v[50:51] op_sel_hi:[1,0]
	v_pk_mul_f32 v[44:45], v[44:45], v[50:51] op_sel_hi:[1,0]
	v_and_b32_e32 v48, 0x1fffff8, v48
	v_cvt_pk_bf16_f32 v44, v44, v45
	v_cvt_pk_bf16_f32 v45, v46, v47
	v_lshl_add_u64 v[46:47], s[4:5], 0, v[52:53]
	v_add_u32_e32 v48, s56, v48
	v_lshl_add_u64 v[46:47], v[46:47], 0, s[58:59]
	v_lshl_add_u32 v48, v48, 7, v153
	v_lshl_add_u64 v[46:47], v[46:47], 0, s[62:63]
	v_lshl_add_u64 v[46:47], v[46:47], 0, v[124:125]
	v_ashrrev_i32_e32 v49, 31, v48
	global_store_dwordx2 v[46:47], v[44:45], off
	v_lshlrev_b64 v[44:45], 12, v[48:49]
	v_lshl_add_u64 v[44:45], s[42:43], 0, v[44:45]
	v_lshlrev_b32_e32 v136, 1, v51
	v_pk_mul_f32 v[36:37], v[36:37], v[50:51] op_sel_hi:[1,0]
	v_lshl_add_u64 v[44:45], v[44:45], 0, v[136:137]
	v_cvt_pk_bf16_f32 v49, v36, v37
	v_add_co_u32_e32 v36, vcc, s79, v44
	v_pk_mul_f32 v[38:39], v[38:39], v[50:51] op_sel_hi:[1,0]
	s_nop 0
	v_addc_co_u32_e32 v37, vcc, 0, v45, vcc
	v_cvt_pk_bf16_f32 v38, v38, v39
	v_add_co_u32_e32 v36, vcc, s44, v44
	s_nop 0
	v_addc_co_u32_e32 v37, vcc, 0, v45, vcc
	v_add_co_u32_e32 v36, vcc, s80, v44
	v_pk_mul_f32 v[32:33], v[32:33], v[50:51] op_sel_hi:[1,0]
	s_nop 0
	v_addc_co_u32_e32 v37, vcc, 0, v45, vcc
	s_nop 1
	v_mov_b32_dpp v246, v49 quad_perm:[1,0,3,2] row_mask:0xf bank_mask:0xf
	v_mov_b32_dpp v247, v38 quad_perm:[1,0,3,2] row_mask:0xf bank_mask:0xf
	v_lshl_add_u64 v[254:255], v[44:45], 0, v[250:251]
	v_perm_b32 v248, v246, v49, v244
	v_perm_b32 v249, v247, v38, v244
	v_bfi_b32 v246, v245, v248, v249
	s_nop 1
	v_mov_b32_dpp v247, v246 quad_perm:[2,3,0,1] row_mask:0xf bank_mask:0xf
	s_nop 0
	v_bfi_b32 v252, v245, v247, v248
	v_bfi_b32 v253, v245, v249, v247
; __device__ __forceinline__ unsigned cvt_pk(float lo, float hi) { unsigned r; asm volatile("v_cvt_pk_bf16_f32 %0, %1, %2" : "=v"(r) : "v"(lo), "v"(hi)); return r; }
; __device__ __forceinline__ u32x2 pack4(f32x4 v) { u32x2 r; r.x = cvt_pk(v[0], v[1]); r.y = cvt_pk(v[2], v[3]); return r; }
; #define FOR_AI_M _Pragma("unroll") for (int ai = 0; ai < 2; ++ai) _Pragma("unroll") for (int m = 0; m < 4; ++m)
;     __device__ __forceinline__ void operator()(EPI_ARGS) const {
;         FOR_AI_M {
;             const int row = u.pm * 256 + ai * 128 + wr * 64 + m * 16 + fr;
;             {
;                 const float rs = rsqrtf(ssq_kv[row] * (1.0f / 256.0f) + EPS);
;                 const int b = row >> 11, t = row & 2047;
; #pragma unroll
;                 for (int n = 0; n < 2; ++n) {
;                     *(u32x2*)(KN + ((size_t)row * 1024 + u.pn * 128 + wc * 32 + n * 16 + 4 * fq)) = pack4(acc[ai][0][m][n] * rs);
;                     const f32x4 v = acc[ai][1][m][n] * rs; const int d = wc * 32 + n * 16 + 4 * fq;
;                     bf16_t* vp = VT + ((size_t)((b * 8 + u.pn) * 128 + d)) * 2048 + t;
;                     const unsigned w0 = cvt_pk(v[0], v[1]), w1 = cvt_pk(v[2], v[3]);
;                     vp[0] = (bf16_t)(w0 & 0xffff); vp[2048] = (bf16_t)(w0 >> 16); vp[2 * 2048] = (bf16_t)(w1 & 0xffff); vp[3 * 2048] = (bf16_t)(w1 >> 16);
;                 }
	global_store_dwordx2 v[254:255], v[252:253], off
	v_pk_mul_f32 v[36:37], v[42:43], v[50:51] op_sel_hi:[1,0]
	v_pk_mul_f32 v[38:39], v[40:41], v[50:51] op_sel_hi:[1,0]
	v_pk_mul_f32 v[34:35], v[34:35], v[50:51] op_sel_hi:[1,0]
	v_cvt_pk_bf16_f32 v38, v38, v39
	v_cvt_pk_bf16_f32 v39, v36, v37
	v_add_u32_e32 v36, 16, v48
	v_ashrrev_i32_e32 v37, 31, v36
	v_lshlrev_b64 v[36:37], 12, v[36:37]
	v_lshl_add_u64 v[36:37], s[42:43], 0, v[36:37]
	v_lshl_add_u64 v[36:37], v[36:37], 0, v[136:137]
	global_store_dwordx2 v[46:47], v[38:39], off offset:32
	v_cvt_pk_bf16_f32 v38, v32, v33
	v_add_co_u32_e32 v32, vcc, s79, v36
	v_cvt_pk_bf16_f32 v34, v34, v35
	s_nop 0
	v_addc_co_u32_e32 v33, vcc, 0, v37, vcc
	v_add_co_u32_e32 v32, vcc, s44, v36
	s_nop 1
	v_addc_co_u32_e32 v33, vcc, 0, v37, vcc
	v_add_co_u32_e32 v32, vcc, s80, v36
	s_nop 1
	v_addc_co_u32_e32 v33, vcc, 0, v37, vcc
	s_nop 1
	v_mov_b32_dpp v246, v38 quad_perm:[1,0,3,2] row_mask:0xf bank_mask:0xf
	v_mov_b32_dpp v247, v34 quad_perm:[1,0,3,2] row_mask:0xf bank_mask:0xf
	v_lshl_add_u64 v[254:255], v[36:37], 0, v[250:251]
	v_perm_b32 v248, v246, v38, v244
	v_perm_b32 v249, v247, v34, v244
	v_bfi_b32 v246, v245, v248, v249
	s_nop 1
	v_mov_b32_dpp v247, v246 quad_perm:[2,3,0,1] row_mask:0xf bank_mask:0xf
	s_nop 0
	v_bfi_b32 v252, v245, v247, v248
	v_bfi_b32 v253, v245, v249, v247
	global_store_dwordx2 v[254:255], v[252:253], off
	v_add_u32_e32 v32, 0xa0, v142
	v_ashrrev_i32_e32 v33, 31, v32
	v_lshl_add_u64 v[34:35], v[32:33], 2, s[20:21]
	global_load_dword v34, v[34:35], off
	v_lshlrev_b64 v[36:37], 11, v[32:33]
	s_waitcnt vmcnt(0)
	v_fmamk_f32 v34, v34, 0x3b800000, v152
	v_cmp_gt_f32_e32 vcc, s78, v34
	v_mul_f32_e32 v35, 0x4b800000, v34
	s_nop 0
	v_cndmask_b32_e32 v34, v34, v35, vcc
	v_rsq_f32_e32 v34, v34
	s_nop 0
	v_mul_f32_e32 v35, 0x45800000, v34
	v_cndmask_b32_e32 v34, v34, v35, vcc
	v_and_b32_e32 v35, 0x7ff, v32
	v_ashrrev_i32_e32 v32, 8, v32
	v_pk_mul_f32 v[30:31], v[30:31], v[34:35] op_sel_hi:[1,0]
	v_pk_mul_f32 v[28:29], v[28:29], v[34:35] op_sel_hi:[1,0]
	v_and_b32_e32 v32, 0x1fffff8, v32
	v_cvt_pk_bf16_f32 v28, v28, v29
	v_cvt_pk_bf16_f32 v29, v30, v31
	v_lshl_add_u64 v[30:31], s[4:5], 0, v[36:37]
	v_add_u32_e32 v32, s56, v32
	v_lshl_add_u64 v[30:31], v[30:31], 0, s[58:59]
	v_lshl_add_u32 v32, v32, 7, v153
	v_lshl_add_u64 v[30:31], v[30:31], 0, s[62:63]
	v_lshl_add_u64 v[30:31], v[30:31], 0, v[124:125]
	v_ashrrev_i32_e32 v33, 31, v32
	global_store_dwordx2 v[30:31], v[28:29], off
	v_lshlrev_b64 v[28:29], 12, v[32:33]
	v_lshl_add_u64 v[28:29], s[42:43], 0, v[28:29]
	v_lshlrev_b32_e32 v136, 1, v35
	v_pk_mul_f32 v[20:21], v[20:21], v[34:35] op_sel_hi:[1,0]
	v_lshl_add_u64 v[28:29], v[28:29], 0, v[136:137]
	v_cvt_pk_bf16_f32 v33, v20, v21
	v_add_co_u32_e32 v20, vcc, s79, v28
	v_pk_mul_f32 v[22:23], v[22:23], v[34:35] op_sel_hi:[1,0]
	s_nop 0
	v_addc_co_u32_e32 v21, vcc, 0, v29, vcc
	v_cvt_pk_bf16_f32 v22, v22, v23
	v_add_co_u32_e32 v20, vcc, s44, v28
	s_nop 0
	v_addc_co_u32_e32 v21, vcc, 0, v29, vcc
	v_add_co_u32_e32 v20, vcc, s80, v28
	v_pk_mul_f32 v[16:17], v[16:17], v[34:35] op_sel_hi:[1,0]
	s_nop 0
	v_addc_co_u32_e32 v21, vcc, 0, v29, vcc
	s_nop 1
	v_mov_b32_dpp v246, v33 quad_perm:[1,0,3,2] row_mask:0xf bank_mask:0xf
	v_mov_b32_dpp v247, v22 quad_perm:[1,0,3,2] row_mask:0xf bank_mask:0xf
	v_lshl_add_u64 v[254:255], v[28:29], 0, v[250:251]
	v_perm_b32 v248, v246, v33, v244
	v_perm_b32 v249, v247, v22, v244
	v_bfi_b32 v246, v245, v248, v249
	s_nop 1
	v_mov_b32_dpp v247, v246 quad_perm:[2,3,0,1] row_mask:0xf bank_mask:0xf
	s_nop 0
	v_bfi_b32 v252, v245, v247, v248
	v_bfi_b32 v253, v245, v249, v247
	global_store_dwordx2 v[254:255], v[252:253], off
	v_pk_mul_f32 v[20:21], v[26:27], v[34:35] op_sel_hi:[1,0]
	v_pk_mul_f32 v[22:23], v[24:25], v[34:35] op_sel_hi:[1,0]
	v_pk_mul_f32 v[18:19], v[18:19], v[34:35] op_sel_hi:[1,0]
	v_cvt_pk_bf16_f32 v22, v22, v23
	v_cvt_pk_bf16_f32 v23, v20, v21
	v_add_u32_e32 v20, 16, v32
	v_ashrrev_i32_e32 v21, 31, v20
	v_lshlrev_b64 v[20:21], 12, v[20:21]
	v_lshl_add_u64 v[20:21], s[42:43], 0, v[20:21]
	v_lshl_add_u64 v[20:21], v[20:21], 0, v[136:137]
	global_store_dwordx2 v[30:31], v[22:23], off offset:32
	v_cvt_pk_bf16_f32 v22, v16, v17
	v_add_co_u32_e32 v16, vcc, s79, v20
	v_cvt_pk_bf16_f32 v18, v18, v19
	s_nop 0
	v_addc_co_u32_e32 v17, vcc, 0, v21, vcc
	v_add_co_u32_e32 v16, vcc, s44, v20
	s_nop 1
	v_addc_co_u32_e32 v17, vcc, 0, v21, vcc
	v_add_co_u32_e32 v16, vcc, s80, v20
	s_nop 1
	v_addc_co_u32_e32 v17, vcc, 0, v21, vcc
	s_nop 1
	v_mov_b32_dpp v246, v22 quad_perm:[1,0,3,2] row_mask:0xf bank_mask:0xf
	v_mov_b32_dpp v247, v18 quad_perm:[1,0,3,2] row_mask:0xf bank_mask:0xf
	v_lshl_add_u64 v[254:255], v[20:21], 0, v[250:251]
	v_perm_b32 v248, v246, v22, v244
	v_perm_b32 v249, v247, v18, v244
	v_bfi_b32 v246, v245, v248, v249
	s_nop 1
	v_mov_b32_dpp v247, v246 quad_perm:[2,3,0,1] row_mask:0xf bank_mask:0xf
	s_nop 0
	v_bfi_b32 v252, v245, v247, v248
	v_bfi_b32 v253, v245, v249, v247
	global_store_dwordx2 v[254:255], v[252:253], off
	v_add_u32_e32 v16, 0xb0, v142
	v_ashrrev_i32_e32 v17, 31, v16
	v_lshl_add_u64 v[18:19], v[16:17], 2, s[20:21]
	global_load_dword v18, v[18:19], off
	v_lshlrev_b64 v[20:21], 11, v[16:17]
	s_waitcnt vmcnt(0)
; __device__ __forceinline__ unsigned cvt_pk(float lo, float hi) { unsigned r; asm volatile("v_cvt_pk_bf16_f32 %0, %1, %2" : "=v"(r) : "v"(lo), "v"(hi)); return r; }
; __device__ __forceinline__ u32x2 pack4(f32x4 v) { u32x2 r; r.x = cvt_pk(v[0], v[1]); r.y = cvt_pk(v[2], v[3]); return r; }
; #define FOR_AI_M _Pragma("unroll") for (int ai = 0; ai < 2; ++ai) _Pragma("unroll") for (int m = 0; m < 4; ++m)
;     __device__ __forceinline__ void operator()(EPI_ARGS) const {
;         FOR_AI_M {
;             const int row = u.pm * 256 + ai * 128 + wr * 64 + m * 16 + fr;
;             {
;                 const float rs = rsqrtf(ssq_kv[row] * (1.0f / 256.0f) + EPS);
;                 const int b = row >> 11, t = row & 2047;
; #pragma unroll
;                 for (int n = 0; n < 2; ++n) {
;                     *(u32x2*)(KN + ((size_t)row * 1024 + u.pn * 128 + wc * 32 + n * 16 + 4 * fq)) = pack4(acc[ai][0][m][n] * rs);
;                     const f32x4 v = acc[ai][1][m][n] * rs; const int d = wc * 32 + n * 16 + 4 * fq;
;                     bf16_t* vp = VT + ((size_t)((b * 8 + u.pn) * 128 + d)) * 2048 + t;
;                     const unsigned w0 = cvt_pk(v[0], v[1]), w1 = cvt_pk(v[2], v[3]);
;                     vp[0] = (bf16_t)(w0 & 0xffff); vp[2048] = (bf16_t)(w0 >> 16); vp[2 * 2048] = (bf16_t)(w1 & 0xffff); vp[3 * 2048] = (bf16_t)(w1 >> 16);
;                 }
	v_fmamk_f32 v18, v18, 0x3b800000, v152
	v_cmp_gt_f32_e32 vcc, s78, v18
	v_mul_f32_e32 v19, 0x4b800000, v18
	s_nop 0
	v_cndmask_b32_e32 v18, v18, v19, vcc
	v_rsq_f32_e32 v18, v18
	s_nop 0
	v_mul_f32_e32 v19, 0x45800000, v18
	v_cndmask_b32_e32 v18, v18, v19, vcc
	v_and_b32_e32 v19, 0x7ff, v16
	v_ashrrev_i32_e32 v16, 8, v16
	v_pk_mul_f32 v[14:15], v[14:15], v[18:19] op_sel_hi:[1,0]
	v_pk_mul_f32 v[12:13], v[12:13], v[18:19] op_sel_hi:[1,0]
	v_and_b32_e32 v16, 0x1fffff8, v16
	v_cvt_pk_bf16_f32 v12, v12, v13
	v_cvt_pk_bf16_f32 v13, v14, v15
	v_lshl_add_u64 v[14:15], s[4:5], 0, v[20:21]
	v_add_u32_e32 v16, s56, v16
	v_lshl_add_u64 v[14:15], v[14:15], 0, s[58:59]
	v_lshl_add_u32 v16, v16, 7, v153
	v_lshl_add_u64 v[14:15], v[14:15], 0, s[62:63]
	v_lshl_add_u64 v[14:15], v[14:15], 0, v[124:125]
	v_ashrrev_i32_e32 v17, 31, v16
	global_store_dwordx2 v[14:15], v[12:13], off
	v_lshlrev_b64 v[12:13], 12, v[16:17]
	v_lshl_add_u64 v[12:13], s[42:43], 0, v[12:13]
	v_lshlrev_b32_e32 v136, 1, v19
	v_pk_mul_f32 v[4:5], v[4:5], v[18:19] op_sel_hi:[1,0]
	v_lshl_add_u64 v[12:13], v[12:13], 0, v[136:137]
	v_cvt_pk_bf16_f32 v17, v4, v5
	v_add_co_u32_e32 v4, vcc, s79, v12
	v_pk_mul_f32 v[6:7], v[6:7], v[18:19] op_sel_hi:[1,0]
	s_nop 0
	v_addc_co_u32_e32 v5, vcc, 0, v13, vcc
	v_cvt_pk_bf16_f32 v6, v6, v7
	v_add_co_u32_e32 v4, vcc, s44, v12
	s_nop 0
	v_addc_co_u32_e32 v5, vcc, 0, v13, vcc
	v_add_co_u32_e32 v4, vcc, s80, v12
	v_pk_mul_f32 v[0:1], v[0:1], v[18:19] op_sel_hi:[1,0]
	s_nop 0
	v_addc_co_u32_e32 v5, vcc, 0, v13, vcc
	s_nop 1
	v_mov_b32_dpp v246, v17 quad_perm:[1,0,3,2] row_mask:0xf bank_mask:0xf
	v_mov_b32_dpp v247, v6 quad_perm:[1,0,3,2] row_mask:0xf bank_mask:0xf
	v_lshl_add_u64 v[254:255], v[12:13], 0, v[250:251]
	v_perm_b32 v248, v246, v17, v244
	v_perm_b32 v249, v247, v6, v244
	v_bfi_b32 v246, v245, v248, v249
	s_nop 1
	v_mov_b32_dpp v247, v246 quad_perm:[2,3,0,1] row_mask:0xf bank_mask:0xf
	s_nop 0
	v_bfi_b32 v252, v245, v247, v248
	v_bfi_b32 v253, v245, v249, v247
	global_store_dwordx2 v[254:255], v[252:253], off
	v_pk_mul_f32 v[4:5], v[10:11], v[18:19] op_sel_hi:[1,0]
	v_pk_mul_f32 v[6:7], v[8:9], v[18:19] op_sel_hi:[1,0]
	v_pk_mul_f32 v[2:3], v[2:3], v[18:19] op_sel_hi:[1,0]
	v_cvt_pk_bf16_f32 v6, v6, v7
	v_cvt_pk_bf16_f32 v7, v4, v5
	v_add_u32_e32 v4, 16, v16
	v_ashrrev_i32_e32 v5, 31, v4
	v_lshlrev_b64 v[4:5], 12, v[4:5]
	v_lshl_add_u64 v[4:5], s[42:43], 0, v[4:5]
	v_lshl_add_u64 v[4:5], v[4:5], 0, v[136:137]
	global_store_dwordx2 v[14:15], v[6:7], off offset:32
	v_cvt_pk_bf16_f32 v6, v0, v1
	v_add_co_u32_e32 v0, vcc, 0x1000, v4
	v_cvt_pk_bf16_f32 v2, v2, v3
	s_nop 0
	v_addc_co_u32_e32 v1, vcc, 0, v5, vcc
	v_add_co_u32_e32 v0, vcc, 0x2000, v4
	s_nop 1
	v_addc_co_u32_e32 v1, vcc, 0, v5, vcc
	v_add_co_u32_e32 v0, vcc, 0x3000, v4
	s_nop 1
	v_addc_co_u32_e32 v1, vcc, 0, v5, vcc
	s_andn2_b64 vcc, exec, s[46:47]
	s_nop 1
	v_mov_b32_dpp v246, v6 quad_perm:[1,0,3,2] row_mask:0xf bank_mask:0xf
	v_mov_b32_dpp v247, v2 quad_perm:[1,0,3,2] row_mask:0xf bank_mask:0xf
	v_lshl_add_u64 v[254:255], v[4:5], 0, v[250:251]
	v_perm_b32 v248, v246, v6, v244
	v_perm_b32 v249, v247, v2, v244
	v_bfi_b32 v246, v245, v248, v249
	s_nop 1
	v_mov_b32_dpp v247, v246 quad_perm:[2,3,0,1] row_mask:0xf bank_mask:0xf
	s_nop 0
	v_bfi_b32 v252, v245, v247, v248
	v_bfi_b32 v253, v245, v249, v247
	global_store_dwordx2 v[254:255], v[252:253], off
	s_cbranch_vccnz .LBB0_554
	s_andn2_b64 vcc, exec, s[28:29]
	s_cbranch_vccnz .LBB0_553
	s_barrier
	s_branch .LBB0_553
